# v12 with residual loads using default cache policy instead of nt (prefetched lines served from L2 or MALL)
# speedup vs baseline: 1.0057x; 1.0057x over previous
.LBB0_408:
	v_lshl_add_u32 v156, s79, 8, v133
	v_lshl_or_b32 v154, s78, 8, v159
	v_ashrrev_i32_e32 v157, 31, v156
	v_ashrrev_i32_e32 v155, 31, v154
	v_lshlrev_b64 v[162:163], 11, v[156:157]
	v_lshl_add_u64 v[162:163], v[162:163], 0, v[154:155]
	v_lshlrev_b64 v[162:163], 1, v[162:163]
	v_lshl_add_u64 v[174:175], s[54:55], 0, v[162:163]
	v_mov_b32_e32 v252, v162
	global_load_dwordx4 v[170:173], v252, s[54:55]
	global_load_dwordx4 v[178:181], v252, s[54:55] offset:256
	v_add_u32_e32 v253, 0x10000, v252
	global_load_dwordx4 v[182:185], v253, s[54:55]
	global_load_dwordx4 v[186:189], v253, s[54:55] offset:256
	v_add_u32_e32 v253, 0x20000, v252
	global_load_dwordx4 v[194:197], v253, s[54:55]
	global_load_dwordx4 v[198:201], v253, s[54:55] offset:256
	v_add_u32_e32 v253, 0x30000, v252
	global_load_dwordx4 v[202:205], v253, s[54:55]
	global_load_dwordx4 v[206:209], v253, s[54:55] offset:256
	v_add_u32_e32 v253, 0x80000, v252
	global_load_dwordx4 v[210:213], v253, s[54:55]
	global_load_dwordx4 v[214:217], v253, s[54:55] offset:256
	v_add_u32_e32 v253, 0x90000, v252
	global_load_dwordx4 v[218:221], v253, s[54:55]
	global_load_dwordx4 v[222:225], v253, s[54:55] offset:256
	v_add_u32_e32 v253, 0xa0000, v252
	global_load_dwordx4 v[226:229], v253, s[54:55]
	global_load_dwordx4 v[230:233], v253, s[54:55] offset:256
	v_add_u32_e32 v253, 0xb0000, v252
	global_load_dwordx4 v[240:243], v253, s[54:55]
	global_load_dwordx4 v[244:247], v253, s[54:55] offset:256
	v_lshl_add_u64 v[162:163], s[56:57], 0, v[162:163]
	s_waitcnt vmcnt(0)
	v_lshlrev_b32_e32 v176, 16, v170
	v_and_b32_e32 v177, 0xffff0000, v170
	v_lshlrev_b32_e32 v170, 16, v171
	v_and_b32_e32 v171, 0xffff0000, v171
	v_pk_add_f32 v[130:131], v[130:131], v[170:171]
	v_lshlrev_b32_e32 v170, 16, v172
	v_and_b32_e32 v171, 0xffff0000, v172
	v_pk_add_f32 v[128:129], v[128:129], v[176:177]
	v_lshlrev_b32_e32 v172, 16, v173
	v_and_b32_e32 v173, 0xffff0000, v173
	v_pk_add_f32 v[170:171], v[124:125], v[170:171]
	v_cvt_pk_bf16_f32 v124, v128, v129
	v_cvt_pk_bf16_f32 v125, v130, v131
	v_pk_add_f32 v[172:173], v[126:127], v[172:173]
	v_cvt_pk_bf16_f32 v126, v170, v171
	s_nop 0
	v_cvt_pk_bf16_f32 v127, v172, v173
	global_store_dwordx4 v[162:163], v[124:127], off
	s_nop 1
	v_mul_f32_e32 v124, v129, v129
	v_mul_f32_e32 v125, v131, v131
	v_fmac_f32_e32 v124, v128, v128
	v_fmac_f32_e32 v125, v130, v130
	v_add_f32_e32 v124, v124, v125
	v_mul_f32_e32 v125, v171, v171
	v_fmac_f32_e32 v125, v170, v170
	v_add_f32_e32 v124, v125, v124
	v_mul_f32_e32 v125, v173, v173
	v_fmac_f32_e32 v125, v172, v172
	v_add_f32_e32 v130, v125, v124
	v_mov_b64_e32 v[124:125], v[178:179]
	v_mov_b64_e32 v[126:127], v[180:181]
	v_lshlrev_b32_e32 v128, 16, v124
	v_and_b32_e32 v129, 0xffff0000, v124
	v_lshlrev_b32_e32 v124, 16, v125
	v_and_b32_e32 v125, 0xffff0000, v125
	v_pk_add_f32 v[122:123], v[122:123], v[124:125]
	v_lshlrev_b32_e32 v124, 16, v126
	v_and_b32_e32 v125, 0xffff0000, v126
	v_lshlrev_b32_e32 v126, 16, v127
	v_and_b32_e32 v127, 0xffff0000, v127
	v_pk_add_f32 v[120:121], v[120:121], v[128:129]
	v_pk_add_f32 v[126:127], v[118:119], v[126:127]
	v_pk_add_f32 v[124:125], v[116:117], v[124:125]
	v_cvt_pk_bf16_f32 v116, v120, v121
	v_cvt_pk_bf16_f32 v117, v122, v123
	s_nop 0
	v_cvt_pk_bf16_f32 v118, v124, v125
	v_cvt_pk_bf16_f32 v119, v126, v127
	global_store_dwordx4 v[162:163], v[116:119], off offset:256
	s_nop 1
	v_mul_f32_e32 v118, v121, v121
	v_mul_f32_e32 v119, v123, v123
	v_mul_f32_e32 v117, v125, v125
	v_fmac_f32_e32 v118, v120, v120
	v_fmac_f32_e32 v119, v122, v122
	v_mul_f32_e32 v116, v127, v127
	v_fmac_f32_e32 v117, v124, v124
	v_add_f32_e32 v118, v118, v119
	v_fmac_f32_e32 v116, v126, v126
	v_add_f32_e32 v117, v117, v118
	v_add_f32_e32 v116, v116, v117
	v_add_f32_e32 v116, v130, v116
	v_mov_b32_e32 v117, v116
	s_nop 1
	v_permlane16_swap_b32_e32 v116, v117
	v_add_f32_e32 v116, v116, v117
	v_mov_b32_e32 v117, v116
	s_nop 1
	v_permlane32_swap_b32_e32 v116, v117
	s_and_saveexec_b64 s[70:71], s[8:9]
	s_cbranch_execz .LBB0_410
	v_lshl_add_u64 v[118:119], v[156:157], 2, s[58:59]
	v_add_f32_e32 v116, v116, v117
	global_atomic_add_f32 v[118:119], v116, off

.LBB0_858:
	v_lshl_add_u32 v140, s49, 8, v148
	v_lshl_or_b32 v138, s4, 8, v150
	v_ashrrev_i32_e32 v141, 31, v140
	v_ashrrev_i32_e32 v139, 31, v138
	v_lshlrev_b64 v[142:143], 11, v[140:141]
	v_lshl_add_u64 v[142:143], v[142:143], 0, v[138:139]
	v_lshl_add_u64 v[146:147], v[142:143], 1, s[16:17]
	v_lshlrev_b32_e32 v252, 1, v142
	global_load_dwordx4 v[152:155], v252, s[16:17]
	global_load_dwordx4 v[158:161], v252, s[16:17] offset:256
	v_add_u32_e32 v253, 0x10000, v252
	global_load_dwordx4 v[162:165], v253, s[16:17]
	global_load_dwordx4 v[166:169], v253, s[16:17] offset:256
	v_add_u32_e32 v253, 0x20000, v252
	global_load_dwordx4 v[170:173], v253, s[16:17]
	global_load_dwordx4 v[180:183], v253, s[16:17] offset:256
	v_add_u32_e32 v253, 0x30000, v252
	global_load_dwordx4 v[184:187], v253, s[16:17]
	global_load_dwordx4 v[188:191], v253, s[16:17] offset:256
	v_add_u32_e32 v253, 0x80000, v252
	global_load_dwordx4 v[200:203], v253, s[16:17]
	global_load_dwordx4 v[204:207], v253, s[16:17] offset:256
	v_add_u32_e32 v253, 0x90000, v252
	global_load_dwordx4 v[208:211], v253, s[16:17]
	global_load_dwordx4 v[212:215], v253, s[16:17] offset:256
	v_add_u32_e32 v253, 0xa0000, v252
	global_load_dwordx4 v[216:219], v253, s[16:17]
	global_load_dwordx4 v[240:243], v253, s[16:17] offset:256
	v_add_u32_e32 v253, 0xb0000, v252
	global_load_dwordx4 v[244:247], v253, s[16:17]
	global_load_dwordx4 v[248:251], v253, s[16:17] offset:256
	s_andn2_b64 vcc, exec, s[28:29]
	s_waitcnt vmcnt(0)
	v_lshlrev_b32_e32 v144, 16, v152
	v_and_b32_e32 v145, 0xffff0000, v152
	v_lshlrev_b32_e32 v152, 16, v153
	v_and_b32_e32 v153, 0xffff0000, v153
	v_pk_add_f32 v[124:125], v[124:125], v[144:145]
	v_lshlrev_b32_e32 v144, 16, v154
	v_and_b32_e32 v145, 0xffff0000, v154
	v_pk_add_f32 v[126:127], v[126:127], v[152:153]
	v_lshlrev_b32_e32 v152, 16, v155
	v_and_b32_e32 v153, 0xffff0000, v155
	v_pk_add_f32 v[120:121], v[120:121], v[144:145]
	v_cndmask_b32_e64 v144, 0, 1, s[28:29]
	v_pk_add_f32 v[122:123], v[122:123], v[152:153]
	v_cmp_ne_u32_e64 s[12:13], 1, v144
	v_lshl_add_u64 v[144:145], v[142:143], 2, s[18:19]
	s_cbranch_vccnz .LBB0_860
	global_store_dwordx4 v[144:145], v[124:127], off
	global_store_dwordx4 v[144:145], v[120:123], off offset:16
